# 16x16x32-MFMA hand-written attention phase with the same rescale threshold of 8 (compare with the 32x32x16 loop + threshold)
# speedup vs baseline: 1.0509x; 1.0031x over previous
.Latt16_loop:
	s_waitcnt vmcnt(0)
	s_barrier
	ds_read_b128 v[148:151], v222 offset:24576
	ds_read_b128 v[152:155], v222 offset:26624
	s_mov_b32 m0, s46
	ds_read_b128 v[156:159], v222 offset:28672
	global_load_lds_dwordx4 v216, s[42:43]
	s_add_u32 m0, s46, 0x400
	ds_read_b128 v[160:163], v222 offset:30720
	global_load_lds_dwordx4 v217, s[42:43]
	s_mov_b32 m0, s47
	ds_read_b128 v[164:167], v223 offset:24576
	global_load_lds_dwordx4 v218, s[44:45]
	s_add_u32 m0, s47, 0x400
	ds_read_b128 v[168:171], v223 offset:26624
	global_load_lds_dwordx4 v219, s[44:45]
	s_add_u32 m0, s47, 0x800
	ds_read_b128 v[172:175], v223 offset:28672
	global_load_lds_dwordx4 v220, s[44:45]
	s_add_u32 m0, s47, 0xc00
	ds_read_b128 v[176:179], v223 offset:30720
	global_load_lds_dwordx4 v221, s[44:45]
	s_add_u32 s42, s42, 0x18000
	s_addc_u32 s43, s43, 0
	s_add_u32 s44, s44, 0x80
	s_addc_u32 s45, s45, 0
	ds_read_b128 v[180:183], v222 offset:32768
	ds_read_b128 v[184:187], v222 offset:34816
	ds_read_b128 v[188:191], v222 offset:36864
	ds_read_b128 v[192:195], v222 offset:38912
	s_waitcnt lgkmcnt(11)
	v_mfma_f32_16x16x32_bf16 v[68:71], v[148:151], v[100:103], v[116:119]
	v_mfma_f32_16x16x32_bf16 v[76:79], v[148:151], v[108:111], v[120:123]
	ds_read_b128 v[148:151], v222 offset:40960
	s_waitcnt lgkmcnt(11)
	v_mfma_f32_16x16x32_bf16 v[72:75], v[152:155], v[100:103], v[116:119]
	v_mfma_f32_16x16x32_bf16 v[80:83], v[152:155], v[108:111], v[120:123]
	ds_read_b128 v[152:155], v222 offset:43008
	s_waitcnt lgkmcnt(11)
	v_mfma_f32_16x16x32_bf16 v[84:87], v[156:159], v[100:103], v[116:119]
	v_mfma_f32_16x16x32_bf16 v[92:95], v[156:159], v[108:111], v[120:123]
	ds_read_b128 v[156:159], v222 offset:45056
	s_waitcnt lgkmcnt(11)
	v_mfma_f32_16x16x32_bf16 v[88:91], v[160:163], v[100:103], v[116:119]
	v_mfma_f32_16x16x32_bf16 v[96:99], v[160:163], v[108:111], v[120:123]
	ds_read_b128 v[160:163], v222 offset:47104
	s_waitcnt lgkmcnt(11)
	v_mfma_f32_16x16x32_bf16 v[68:71], v[164:167], v[104:107], v[68:71]
	v_mfma_f32_16x16x32_bf16 v[76:79], v[164:167], v[112:115], v[76:79]
	ds_read_b128 v[164:167], v223 offset:32768
	s_waitcnt lgkmcnt(11)
	v_mfma_f32_16x16x32_bf16 v[72:75], v[168:171], v[104:107], v[72:75]
	v_mfma_f32_16x16x32_bf16 v[80:83], v[168:171], v[112:115], v[80:83]
	ds_read_b128 v[168:171], v223 offset:34816
	s_waitcnt lgkmcnt(11)
	v_mfma_f32_16x16x32_bf16 v[84:87], v[172:175], v[104:107], v[84:87]
	v_mfma_f32_16x16x32_bf16 v[92:95], v[172:175], v[112:115], v[92:95]
	ds_read_b128 v[172:175], v223 offset:36864
	s_waitcnt lgkmcnt(11)
	v_mfma_f32_16x16x32_bf16 v[88:91], v[176:179], v[104:107], v[88:91]
	v_mfma_f32_16x16x32_bf16 v[96:99], v[176:179], v[112:115], v[96:99]
	ds_read_b128 v[176:179], v223 offset:38912
	s_nop 7
	v_max3_f32 v200, v68, v69, v70
	v_max3_f32 v201, v71, v72, v73
	v_max3_f32 v202, v74, v75, v84
	v_max3_f32 v203, v85, v86, v87
	v_max3_f32 v204, v88, v89, v90
	v_max3_f32 v200, v200, v201, v91
	v_max3_f32 v202, v202, v203, v204
	v_max_f32_e32 v196, v200, v202
	v_max3_f32 v205, v76, v77, v78
	v_max3_f32 v206, v79, v80, v81
	v_max3_f32 v207, v82, v83, v92
	v_max3_f32 v208, v93, v94, v95
	v_max3_f32 v209, v96, v97, v98
	v_max3_f32 v205, v205, v206, v99
	v_max3_f32 v207, v207, v208, v209
	v_max_f32_e32 v197, v205, v207
	v_max_f32_e32 v198, v196, v197
	v_cmp_lt_f32_e32 vcc, 0x41000000, v198
	s_cbranch_vccnz .Latt16_resc_a
.Latt16_cont_a:
	v_exp_f32_e32 v68, v68
	v_exp_f32_e32 v69, v69
	v_exp_f32_e32 v70, v70
	v_exp_f32_e32 v71, v71
	v_exp_f32_e32 v72, v72
	v_exp_f32_e32 v73, v73
	v_exp_f32_e32 v74, v74
	v_exp_f32_e32 v75, v75
	v_add_f32_e32 v228, v68, v69
	v_add_f32_e32 v228, v228, v70
	v_add_f32_e32 v228, v228, v71
	v_add_f32_e32 v228, v228, v72
	v_add_f32_e32 v228, v228, v73
	v_add_f32_e32 v228, v228, v74
	v_add_f32_e32 v228, v228, v75
	v_cvt_pk_bf16_f32 v68, v68, v69
	v_cvt_pk_bf16_f32 v69, v70, v71
	v_cvt_pk_bf16_f32 v70, v72, v73
	v_cvt_pk_bf16_f32 v71, v74, v75
	v_exp_f32_e32 v76, v76
	v_exp_f32_e32 v77, v77
	v_exp_f32_e32 v78, v78
	v_exp_f32_e32 v79, v79
	v_exp_f32_e32 v80, v80
	v_exp_f32_e32 v81, v81
	v_exp_f32_e32 v82, v82
	v_exp_f32_e32 v83, v83
	v_add_f32_e32 v229, v76, v77
	v_add_f32_e32 v229, v229, v78
	v_add_f32_e32 v229, v229, v79
	v_add_f32_e32 v229, v229, v80
	v_add_f32_e32 v229, v229, v81
	v_add_f32_e32 v229, v229, v82
	v_add_f32_e32 v229, v229, v83
	v_cvt_pk_bf16_f32 v76, v76, v77
	v_cvt_pk_bf16_f32 v77, v78, v79
	v_cvt_pk_bf16_f32 v78, v80, v81
	v_cvt_pk_bf16_f32 v79, v82, v83
	v_exp_f32_e32 v84, v84
	v_exp_f32_e32 v85, v85
	s_waitcnt lgkmcnt(11)
	v_mfma_f32_16x16x32_bf16 v[4:7], v[180:183], v[68:71], v[4:7]
	v_exp_f32_e32 v86, v86
	v_exp_f32_e32 v87, v87
	v_mfma_f32_16x16x32_bf16 v[8:11], v[180:183], v[76:79], v[8:11]
	v_exp_f32_e32 v88, v88
	v_exp_f32_e32 v89, v89
	ds_read_b128 v[180:183], v223 offset:40960
	s_waitcnt lgkmcnt(11)
	v_mfma_f32_16x16x32_bf16 v[12:15], v[184:187], v[68:71], v[12:15]
	v_exp_f32_e32 v90, v90
	v_exp_f32_e32 v91, v91
	v_mfma_f32_16x16x32_bf16 v[16:19], v[184:187], v[76:79], v[16:19]
	v_add_f32_e32 v228, v228, v84
	v_add_f32_e32 v228, v228, v85
	v_add_f32_e32 v228, v228, v86
	v_add_f32_e32 v228, v228, v87
	ds_read_b128 v[184:187], v223 offset:43008
	s_waitcnt lgkmcnt(11)
	v_mfma_f32_16x16x32_bf16 v[20:23], v[188:191], v[68:71], v[20:23]
	v_add_f32_e32 v228, v228, v88
	v_add_f32_e32 v228, v228, v89
	v_add_f32_e32 v228, v228, v90
	v_add_f32_e32 v228, v228, v91
	v_mfma_f32_16x16x32_bf16 v[24:27], v[188:191], v[76:79], v[24:27]
	v_cvt_pk_bf16_f32 v84, v84, v85
	v_cvt_pk_bf16_f32 v85, v86, v87
	v_cvt_pk_bf16_f32 v86, v88, v89
	v_cvt_pk_bf16_f32 v87, v90, v91
	ds_read_b128 v[188:191], v223 offset:45056
	s_waitcnt lgkmcnt(11)
	v_mfma_f32_16x16x32_bf16 v[28:31], v[192:195], v[68:71], v[28:31]
	v_exp_f32_e32 v92, v92
	v_exp_f32_e32 v93, v93
	v_mfma_f32_16x16x32_bf16 v[32:35], v[192:195], v[76:79], v[32:35]
	v_exp_f32_e32 v94, v94
	v_exp_f32_e32 v95, v95
	ds_read_b128 v[192:195], v223 offset:47104
	s_waitcnt lgkmcnt(11)
	v_mfma_f32_16x16x32_bf16 v[36:39], v[148:151], v[68:71], v[36:39]
	v_exp_f32_e32 v96, v96
	v_exp_f32_e32 v97, v97
	v_mfma_f32_16x16x32_bf16 v[40:43], v[148:151], v[76:79], v[40:43]
	v_exp_f32_e32 v98, v98
	v_exp_f32_e32 v99, v99
	s_waitcnt lgkmcnt(10)
	v_mfma_f32_16x16x32_bf16 v[44:47], v[152:155], v[68:71], v[44:47]
	v_add_f32_e32 v229, v229, v92
	v_add_f32_e32 v229, v229, v93
	v_add_f32_e32 v229, v229, v94
	v_add_f32_e32 v229, v229, v95
	v_mfma_f32_16x16x32_bf16 v[48:51], v[152:155], v[76:79], v[48:51]
	v_add_f32_e32 v229, v229, v96
	v_add_f32_e32 v229, v229, v97
	v_add_f32_e32 v229, v229, v98
	v_add_f32_e32 v229, v229, v99
	s_waitcnt lgkmcnt(9)
	v_mfma_f32_16x16x32_bf16 v[52:55], v[156:159], v[68:71], v[52:55]
	v_cvt_pk_bf16_f32 v92, v92, v93
	v_cvt_pk_bf16_f32 v93, v94, v95
	v_cvt_pk_bf16_f32 v94, v96, v97
	v_cvt_pk_bf16_f32 v95, v98, v99
	v_mfma_f32_16x16x32_bf16 v[56:59], v[156:159], v[76:79], v[56:59]
	s_waitcnt lgkmcnt(8)
	v_mfma_f32_16x16x32_bf16 v[60:63], v[160:163], v[68:71], v[60:63]
	v_mfma_f32_16x16x32_bf16 v[64:67], v[160:163], v[76:79], v[64:67]
	s_nop 1
	s_waitcnt lgkmcnt(7)
	v_mfma_f32_16x16x32_bf16 v[4:7], v[164:167], v[84:87], v[4:7]
	v_mfma_f32_16x16x32_bf16 v[8:11], v[164:167], v[92:95], v[8:11]
	s_waitcnt lgkmcnt(6)
	v_mfma_f32_16x16x32_bf16 v[12:15], v[168:171], v[84:87], v[12:15]
	v_mfma_f32_16x16x32_bf16 v[16:19], v[168:171], v[92:95], v[16:19]
	s_waitcnt lgkmcnt(5)
	v_mfma_f32_16x16x32_bf16 v[20:23], v[172:175], v[84:87], v[20:23]
	v_mfma_f32_16x16x32_bf16 v[24:27], v[172:175], v[92:95], v[24:27]
	s_waitcnt lgkmcnt(4)
	v_mfma_f32_16x16x32_bf16 v[28:31], v[176:179], v[84:87], v[28:31]
	v_mfma_f32_16x16x32_bf16 v[32:35], v[176:179], v[92:95], v[32:35]
	s_waitcnt lgkmcnt(3)
	v_mfma_f32_16x16x32_bf16 v[36:39], v[180:183], v[84:87], v[36:39]
	v_mfma_f32_16x16x32_bf16 v[40:43], v[180:183], v[92:95], v[40:43]
	s_waitcnt lgkmcnt(2)
	v_mfma_f32_16x16x32_bf16 v[44:47], v[184:187], v[84:87], v[44:47]
	v_mfma_f32_16x16x32_bf16 v[48:51], v[184:187], v[92:95], v[48:51]
	s_waitcnt lgkmcnt(1)
	v_mfma_f32_16x16x32_bf16 v[52:55], v[188:191], v[84:87], v[52:55]
	v_mfma_f32_16x16x32_bf16 v[56:59], v[188:191], v[92:95], v[56:59]
	s_waitcnt lgkmcnt(0)
	v_mfma_f32_16x16x32_bf16 v[60:63], v[192:195], v[84:87], v[60:63]
	v_mfma_f32_16x16x32_bf16 v[64:67], v[192:195], v[92:95], v[64:67]
	v_add_f32_e32 v126, v126, v228
	v_add_f32_e32 v127, v127, v229
	s_waitcnt vmcnt(0)
	s_barrier
	ds_read_b128 v[148:151], v222 offset:0
	ds_read_b128 v[152:155], v222 offset:2048
	s_add_u32 m0, s46, 0x6000
	ds_read_b128 v[156:159], v222 offset:4096
	global_load_lds_dwordx4 v216, s[42:43]
	s_add_u32 m0, s46, 0x6400
	ds_read_b128 v[160:163], v222 offset:6144
	global_load_lds_dwordx4 v217, s[42:43]
	s_add_u32 m0, s47, 0x6000
	ds_read_b128 v[164:167], v223 offset:0
	global_load_lds_dwordx4 v218, s[44:45]
	s_add_u32 m0, s47, 0x6400
	ds_read_b128 v[168:171], v223 offset:2048
	global_load_lds_dwordx4 v219, s[44:45]
	s_add_u32 m0, s47, 0x6800
	ds_read_b128 v[172:175], v223 offset:4096
	global_load_lds_dwordx4 v220, s[44:45]
	s_add_u32 m0, s47, 0x6c00
	ds_read_b128 v[176:179], v223 offset:6144
	global_load_lds_dwordx4 v221, s[44:45]
	s_add_u32 s42, s42, 0x18000
	s_addc_u32 s43, s43, 0
	s_add_u32 s44, s44, 0x80
	s_addc_u32 s45, s45, 0
	ds_read_b128 v[180:183], v222 offset:8192
	ds_read_b128 v[184:187], v222 offset:10240
	ds_read_b128 v[188:191], v222 offset:12288
	ds_read_b128 v[192:195], v222 offset:14336
	s_waitcnt lgkmcnt(11)
	v_mfma_f32_16x16x32_bf16 v[68:71], v[148:151], v[100:103], v[116:119]
	v_mfma_f32_16x16x32_bf16 v[76:79], v[148:151], v[108:111], v[120:123]
	ds_read_b128 v[148:151], v222 offset:16384
	s_waitcnt lgkmcnt(11)
	v_mfma_f32_16x16x32_bf16 v[72:75], v[152:155], v[100:103], v[116:119]
	v_mfma_f32_16x16x32_bf16 v[80:83], v[152:155], v[108:111], v[120:123]
	ds_read_b128 v[152:155], v222 offset:18432
	s_waitcnt lgkmcnt(11)
	v_mfma_f32_16x16x32_bf16 v[84:87], v[156:159], v[100:103], v[116:119]
	v_mfma_f32_16x16x32_bf16 v[92:95], v[156:159], v[108:111], v[120:123]
	ds_read_b128 v[156:159], v222 offset:20480
	s_waitcnt lgkmcnt(11)
	v_mfma_f32_16x16x32_bf16 v[88:91], v[160:163], v[100:103], v[116:119]
	v_mfma_f32_16x16x32_bf16 v[96:99], v[160:163], v[108:111], v[120:123]
	ds_read_b128 v[160:163], v222 offset:22528
	s_waitcnt lgkmcnt(11)
	v_mfma_f32_16x16x32_bf16 v[68:71], v[164:167], v[104:107], v[68:71]
	v_mfma_f32_16x16x32_bf16 v[76:79], v[164:167], v[112:115], v[76:79]
	ds_read_b128 v[164:167], v223 offset:8192
	s_waitcnt lgkmcnt(11)
	v_mfma_f32_16x16x32_bf16 v[72:75], v[168:171], v[104:107], v[72:75]
	v_mfma_f32_16x16x32_bf16 v[80:83], v[168:171], v[112:115], v[80:83]
	ds_read_b128 v[168:171], v223 offset:10240
	s_waitcnt lgkmcnt(11)
	v_mfma_f32_16x16x32_bf16 v[84:87], v[172:175], v[104:107], v[84:87]
	v_mfma_f32_16x16x32_bf16 v[92:95], v[172:175], v[112:115], v[92:95]
	ds_read_b128 v[172:175], v223 offset:12288
	s_waitcnt lgkmcnt(11)
	v_mfma_f32_16x16x32_bf16 v[88:91], v[176:179], v[104:107], v[88:91]
	v_mfma_f32_16x16x32_bf16 v[96:99], v[176:179], v[112:115], v[96:99]
	ds_read_b128 v[176:179], v223 offset:14336
	s_nop 7
	v_max3_f32 v200, v68, v69, v70
	v_max3_f32 v201, v71, v72, v73
	v_max3_f32 v202, v74, v75, v84
	v_max3_f32 v203, v85, v86, v87
	v_max3_f32 v204, v88, v89, v90
	v_max3_f32 v200, v200, v201, v91
	v_max3_f32 v202, v202, v203, v204
	v_max_f32_e32 v196, v200, v202
	v_max3_f32 v205, v76, v77, v78
	v_max3_f32 v206, v79, v80, v81
	v_max3_f32 v207, v82, v83, v92
	v_max3_f32 v208, v93, v94, v95
	v_max3_f32 v209, v96, v97, v98
	v_max3_f32 v205, v205, v206, v99
	v_max3_f32 v207, v207, v208, v209
	v_max_f32_e32 v197, v205, v207
	v_max_f32_e32 v198, v196, v197
	v_cmp_lt_f32_e32 vcc, 0x41000000, v198
	s_cbranch_vccnz .Latt16_resc_b
.Latt16_cont_b:
	v_exp_f32_e32 v68, v68
	v_exp_f32_e32 v69, v69
	v_exp_f32_e32 v70, v70
	v_exp_f32_e32 v71, v71
	v_exp_f32_e32 v72, v72
	v_exp_f32_e32 v73, v73
	v_exp_f32_e32 v74, v74
	v_exp_f32_e32 v75, v75
	v_add_f32_e32 v228, v68, v69
	v_add_f32_e32 v228, v228, v70
	v_add_f32_e32 v228, v228, v71
	v_add_f32_e32 v228, v228, v72
	v_add_f32_e32 v228, v228, v73
	v_add_f32_e32 v228, v228, v74
	v_add_f32_e32 v228, v228, v75
	v_cvt_pk_bf16_f32 v68, v68, v69
	v_cvt_pk_bf16_f32 v69, v70, v71
	v_cvt_pk_bf16_f32 v70, v72, v73
	v_cvt_pk_bf16_f32 v71, v74, v75
	v_exp_f32_e32 v76, v76
	v_exp_f32_e32 v77, v77
	v_exp_f32_e32 v78, v78
	v_exp_f32_e32 v79, v79
	v_exp_f32_e32 v80, v80
	v_exp_f32_e32 v81, v81
	v_exp_f32_e32 v82, v82
	v_exp_f32_e32 v83, v83
	v_add_f32_e32 v229, v76, v77
	v_add_f32_e32 v229, v229, v78
	v_add_f32_e32 v229, v229, v79
	v_add_f32_e32 v229, v229, v80
	v_add_f32_e32 v229, v229, v81
	v_add_f32_e32 v229, v229, v82
	v_add_f32_e32 v229, v229, v83
	v_cvt_pk_bf16_f32 v76, v76, v77
	v_cvt_pk_bf16_f32 v77, v78, v79
	v_cvt_pk_bf16_f32 v78, v80, v81
	v_cvt_pk_bf16_f32 v79, v82, v83
	v_exp_f32_e32 v84, v84
	v_exp_f32_e32 v85, v85
	s_waitcnt lgkmcnt(11)
	v_mfma_f32_16x16x32_bf16 v[4:7], v[180:183], v[68:71], v[4:7]
	v_exp_f32_e32 v86, v86
	v_exp_f32_e32 v87, v87
	v_mfma_f32_16x16x32_bf16 v[8:11], v[180:183], v[76:79], v[8:11]
	v_exp_f32_e32 v88, v88
	v_exp_f32_e32 v89, v89
	ds_read_b128 v[180:183], v223 offset:16384
	s_waitcnt lgkmcnt(11)
	v_mfma_f32_16x16x32_bf16 v[12:15], v[184:187], v[68:71], v[12:15]
	v_exp_f32_e32 v90, v90
	v_exp_f32_e32 v91, v91
	v_mfma_f32_16x16x32_bf16 v[16:19], v[184:187], v[76:79], v[16:19]
	v_add_f32_e32 v228, v228, v84
	v_add_f32_e32 v228, v228, v85
	v_add_f32_e32 v228, v228, v86
	v_add_f32_e32 v228, v228, v87
	ds_read_b128 v[184:187], v223 offset:18432
	s_waitcnt lgkmcnt(11)
	v_mfma_f32_16x16x32_bf16 v[20:23], v[188:191], v[68:71], v[20:23]
	v_add_f32_e32 v228, v228, v88
	v_add_f32_e32 v228, v228, v89
	v_add_f32_e32 v228, v228, v90
	v_add_f32_e32 v228, v228, v91
	v_mfma_f32_16x16x32_bf16 v[24:27], v[188:191], v[76:79], v[24:27]
	v_cvt_pk_bf16_f32 v84, v84, v85
	v_cvt_pk_bf16_f32 v85, v86, v87
	v_cvt_pk_bf16_f32 v86, v88, v89
	v_cvt_pk_bf16_f32 v87, v90, v91
	ds_read_b128 v[188:191], v223 offset:20480
	s_waitcnt lgkmcnt(11)
	v_mfma_f32_16x16x32_bf16 v[28:31], v[192:195], v[68:71], v[28:31]
	v_exp_f32_e32 v92, v92
	v_exp_f32_e32 v93, v93
	v_mfma_f32_16x16x32_bf16 v[32:35], v[192:195], v[76:79], v[32:35]
	v_exp_f32_e32 v94, v94
	v_exp_f32_e32 v95, v95
	ds_read_b128 v[192:195], v223 offset:22528
	s_waitcnt lgkmcnt(11)
	v_mfma_f32_16x16x32_bf16 v[36:39], v[148:151], v[68:71], v[36:39]
	v_exp_f32_e32 v96, v96
	v_exp_f32_e32 v97, v97
	v_mfma_f32_16x16x32_bf16 v[40:43], v[148:151], v[76:79], v[40:43]
	v_exp_f32_e32 v98, v98
	v_exp_f32_e32 v99, v99
	s_waitcnt lgkmcnt(10)
	v_mfma_f32_16x16x32_bf16 v[44:47], v[152:155], v[68:71], v[44:47]
	v_add_f32_e32 v229, v229, v92
	v_add_f32_e32 v229, v229, v93
	v_add_f32_e32 v229, v229, v94
	v_add_f32_e32 v229, v229, v95
	v_mfma_f32_16x16x32_bf16 v[48:51], v[152:155], v[76:79], v[48:51]
	v_add_f32_e32 v229, v229, v96
	v_add_f32_e32 v229, v229, v97
	v_add_f32_e32 v229, v229, v98
	v_add_f32_e32 v229, v229, v99
	s_waitcnt lgkmcnt(9)
	v_mfma_f32_16x16x32_bf16 v[52:55], v[156:159], v[68:71], v[52:55]
	v_cvt_pk_bf16_f32 v92, v92, v93
	v_cvt_pk_bf16_f32 v93, v94, v95
	v_cvt_pk_bf16_f32 v94, v96, v97
	v_cvt_pk_bf16_f32 v95, v98, v99
	v_mfma_f32_16x16x32_bf16 v[56:59], v[156:159], v[76:79], v[56:59]
	s_waitcnt lgkmcnt(8)
	v_mfma_f32_16x16x32_bf16 v[60:63], v[160:163], v[68:71], v[60:63]
	v_mfma_f32_16x16x32_bf16 v[64:67], v[160:163], v[76:79], v[64:67]
	s_nop 1
	s_waitcnt lgkmcnt(7)
	v_mfma_f32_16x16x32_bf16 v[4:7], v[164:167], v[84:87], v[4:7]
	v_mfma_f32_16x16x32_bf16 v[8:11], v[164:167], v[92:95], v[8:11]
	s_waitcnt lgkmcnt(6)
	v_mfma_f32_16x16x32_bf16 v[12:15], v[168:171], v[84:87], v[12:15]
	v_mfma_f32_16x16x32_bf16 v[16:19], v[168:171], v[92:95], v[16:19]
	s_waitcnt lgkmcnt(5)
	v_mfma_f32_16x16x32_bf16 v[20:23], v[172:175], v[84:87], v[20:23]
	v_mfma_f32_16x16x32_bf16 v[24:27], v[172:175], v[92:95], v[24:27]
	s_waitcnt lgkmcnt(4)
	v_mfma_f32_16x16x32_bf16 v[28:31], v[176:179], v[84:87], v[28:31]
	v_mfma_f32_16x16x32_bf16 v[32:35], v[176:179], v[92:95], v[32:35]
	s_waitcnt lgkmcnt(3)
	v_mfma_f32_16x16x32_bf16 v[36:39], v[180:183], v[84:87], v[36:39]
	v_mfma_f32_16x16x32_bf16 v[40:43], v[180:183], v[92:95], v[40:43]
	s_waitcnt lgkmcnt(2)
	v_mfma_f32_16x16x32_bf16 v[44:47], v[184:187], v[84:87], v[44:47]
	v_mfma_f32_16x16x32_bf16 v[48:51], v[184:187], v[92:95], v[48:51]
	s_waitcnt lgkmcnt(1)
	v_mfma_f32_16x16x32_bf16 v[52:55], v[188:191], v[84:87], v[52:55]
	v_mfma_f32_16x16x32_bf16 v[56:59], v[188:191], v[92:95], v[56:59]
	s_waitcnt lgkmcnt(0)
	v_mfma_f32_16x16x32_bf16 v[60:63], v[192:195], v[84:87], v[60:63]
	v_mfma_f32_16x16x32_bf16 v[64:67], v[192:195], v[92:95], v[64:67]
	v_add_f32_e32 v126, v126, v228
	v_add_f32_e32 v127, v127, v229
	s_sub_u32 s48, s48, 1
	s_cmp_lg_u32 s48, 0
	s_cbranch_scc1 .Latt16_loop
	s_waitcnt vmcnt(0)
	s_barrier
	ds_read_b128 v[148:151], v222 offset:24576
	ds_read_b128 v[152:155], v222 offset:26624
	ds_read_b128 v[156:159], v222 offset:28672
	ds_read_b128 v[160:163], v222 offset:30720
	ds_read_b128 v[164:167], v223 offset:24576
	ds_read_b128 v[168:171], v223 offset:26624
	ds_read_b128 v[172:175], v223 offset:28672
	ds_read_b128 v[176:179], v223 offset:30720
	ds_read_b128 v[180:183], v222 offset:32768
	ds_read_b128 v[184:187], v222 offset:34816
	ds_read_b128 v[188:191], v222 offset:36864
	ds_read_b128 v[192:195], v222 offset:38912
	s_waitcnt lgkmcnt(11)
	v_mfma_f32_16x16x32_bf16 v[68:71], v[148:151], v[100:103], v[116:119]
	v_mfma_f32_16x16x32_bf16 v[76:79], v[148:151], v[108:111], v[120:123]
	ds_read_b128 v[148:151], v222 offset:40960
	s_waitcnt lgkmcnt(11)
	v_mfma_f32_16x16x32_bf16 v[72:75], v[152:155], v[100:103], v[116:119]
	v_mfma_f32_16x16x32_bf16 v[80:83], v[152:155], v[108:111], v[120:123]
	ds_read_b128 v[152:155], v222 offset:43008
	s_waitcnt lgkmcnt(11)
	v_mfma_f32_16x16x32_bf16 v[84:87], v[156:159], v[100:103], v[116:119]
	v_mfma_f32_16x16x32_bf16 v[92:95], v[156:159], v[108:111], v[120:123]
	ds_read_b128 v[156:159], v222 offset:45056
	s_waitcnt lgkmcnt(11)
	v_mfma_f32_16x16x32_bf16 v[88:91], v[160:163], v[100:103], v[116:119]
	v_mfma_f32_16x16x32_bf16 v[96:99], v[160:163], v[108:111], v[120:123]
	ds_read_b128 v[160:163], v222 offset:47104
	s_waitcnt lgkmcnt(11)
	v_mfma_f32_16x16x32_bf16 v[68:71], v[164:167], v[104:107], v[68:71]
	v_mfma_f32_16x16x32_bf16 v[76:79], v[164:167], v[112:115], v[76:79]
	ds_read_b128 v[164:167], v223 offset:32768
	s_waitcnt lgkmcnt(11)
	v_mfma_f32_16x16x32_bf16 v[72:75], v[168:171], v[104:107], v[72:75]
	v_mfma_f32_16x16x32_bf16 v[80:83], v[168:171], v[112:115], v[80:83]
	ds_read_b128 v[168:171], v223 offset:34816
	s_waitcnt lgkmcnt(11)
	v_mfma_f32_16x16x32_bf16 v[84:87], v[172:175], v[104:107], v[84:87]
	v_mfma_f32_16x16x32_bf16 v[92:95], v[172:175], v[112:115], v[92:95]
	ds_read_b128 v[172:175], v223 offset:36864
	s_waitcnt lgkmcnt(11)
	v_mfma_f32_16x16x32_bf16 v[88:91], v[176:179], v[104:107], v[88:91]
	v_mfma_f32_16x16x32_bf16 v[96:99], v[176:179], v[112:115], v[96:99]
	ds_read_b128 v[176:179], v223 offset:38912
	s_nop 7
	v_max3_f32 v200, v68, v69, v70
	v_max3_f32 v201, v71, v72, v73
	v_max3_f32 v202, v74, v75, v84
	v_max3_f32 v203, v85, v86, v87
	v_max3_f32 v204, v88, v89, v90
	v_max3_f32 v200, v200, v201, v91
	v_max3_f32 v202, v202, v203, v204
	v_max_f32_e32 v196, v200, v202
	v_max3_f32 v205, v76, v77, v78
	v_max3_f32 v206, v79, v80, v81
	v_max3_f32 v207, v82, v83, v92
	v_max3_f32 v208, v93, v94, v95
	v_max3_f32 v209, v96, v97, v98
	v_max3_f32 v205, v205, v206, v99
	v_max3_f32 v207, v207, v208, v209
	v_max_f32_e32 v197, v205, v207
	v_max_f32_e32 v198, v196, v197
	v_cmp_lt_f32_e32 vcc, 0x41000000, v198
	s_cbranch_vccnz .Latt16_resc_l
